# nt (streaming) hint on the final phase's eight output stores (never re-read); on top of the mix epilogue rewrite
# baseline (speedup 1.0000x reference)
; __device__ __forceinline__ float bf_lo(unsigned w) { return __uint_as_float(w << 16); }
; __device__ __forceinline__ float bf_hi(unsigned w) { return __uint_as_float(w & 0xffff0000u); }
; __device__ __forceinline__ void phase12(const Args& a, LAS unsigned char* lds, int G, int wv, float* xout_base = nullptr) {
;     ...
;         _Pragma("unroll 1") for (int rr = 0; rr < 8; ++rr) {
;             const int row = r0 + wave * 8 + rr; const u32x4* fp = (const u32x4*)(F + (size_t)row * 2048); const u32x4* yp = (const u32x4*)(Y + (size_t)row * 4096);
;             const float* xr = x + (size_t)row * 2048; float* xo = OUT + (size_t)row * 2048;
;             u32x4 yw[4], fw[4]; float ssy = 0.f, ssf = 0.f;
; #pragma unroll
;             for (int j = 0; j < 4; ++j) { yw[j] = yp[lane + 64 * j]; fw[j] = __builtin_nontemporal_load(&fp[lane + 64 * j]); }
; #pragma unroll
;             for (int j = 0; j < 4; ++j) {
;                 const float y0 = bf_lo(yw[j].x), y1 = bf_hi(yw[j].x), y2 = bf_lo(yw[j].y), y3 = bf_hi(yw[j].y), y4 = bf_lo(yw[j].z), y5 = bf_hi(yw[j].z), y6 = bf_lo(yw[j].w), y7 = bf_hi(yw[j].w);
;                 ssy += ((y0 * y0 + y1 * y1) + (y2 * y2 + y3 * y3)) + ((y4 * y4 + y5 * y5) + (y6 * y6 + y7 * y7));
;                 const float f0 = bf_lo(fw[j].x), f1 = bf_hi(fw[j].x), f2 = bf_lo(fw[j].y), f3 = bf_hi(fw[j].y), f4 = bf_lo(fw[j].z), f5 = bf_hi(fw[j].z), f6 = bf_lo(fw[j].w), f7 = bf_hi(fw[j].w);
;                 ssf += ((f0 * f0 + f1 * f1) + (f2 * f2 + f3 * f3)) + ((f4 * f4 + f5 * f5) + (f6 * f6 + f7 * f7)); }
.LBB0_1176:
	global_load_dwordx4 v[76:79], v[112:113], off nt
	global_load_dwordx4 v[72:75], v[112:113], off offset:1024 nt
	global_load_dwordx4 v[68:71], v[112:113], off offset:2048 nt
	global_load_dwordx4 v[64:67], v[112:113], off offset:3072 nt
	v_lshl_add_u64 v[80:81], v[114:115], 0, s[12:13]
	v_lshl_add_u64 v[116:117], v[108:109], 0, s[12:13]
	global_load_dwordx4 v[128:131], v[80:81], off
	global_load_dwordx4 v[132:135], v[80:81], off offset:1024
	global_load_dwordx4 v[164:167], v[80:81], off offset:2048
	global_load_dwordx4 v[168:171], v[80:81], off offset:3072
	s_nop 0
	global_load_dwordx4 v[80:83], v[116:117], off offset:16 nt
	global_load_dwordx4 v[84:87], v[116:117], off nt
	v_lshl_add_u64 v[118:119], v[110:111], 0, s[12:13]
	s_add_u32 s12, s12, 0x2000
	s_addc_u32 s13, s13, 0
	v_lshl_add_u64 v[112:113], v[112:113], 0, s[6:7]
	s_cmp_eq_u32 s12, 0x10000
	s_waitcnt vmcnt(9)
	v_and_b32_e32 v175, 0xffff0000, v77
	v_and_b32_e32 v174, 0xffff0000, v76
	v_and_b32_e32 v179, 0xffff0000, v79
	v_and_b32_e32 v178, 0xffff0000, v78
	s_waitcnt vmcnt(8)
	v_and_b32_e32 v141, 0xffff0000, v73
	v_and_b32_e32 v140, 0xffff0000, v72
	v_and_b32_e32 v143, 0xffff0000, v75
	v_and_b32_e32 v142, 0xffff0000, v74
	v_lshlrev_b32_e32 v173, 16, v77
	v_lshlrev_b32_e32 v172, 16, v76
	v_lshlrev_b32_e32 v177, 16, v79
	v_lshlrev_b32_e32 v176, 16, v78
	v_lshlrev_b32_e32 v137, 16, v73
	v_lshlrev_b32_e32 v136, 16, v72
	v_lshlrev_b32_e32 v139, 16, v75
	v_lshlrev_b32_e32 v138, 16, v74
	s_waitcnt vmcnt(7)
	v_and_b32_e32 v121, 0xffff0000, v68
	v_and_b32_e32 v125, 0xffff0000, v69
	v_and_b32_e32 v123, 0xffff0000, v70
	v_and_b32_e32 v127, 0xffff0000, v71
	s_waitcnt vmcnt(5)
	v_and_b32_e32 v183, 0xffff0000, v129
	v_and_b32_e32 v182, 0xffff0000, v128
	v_and_b32_e32 v187, 0xffff0000, v131
	v_and_b32_e32 v186, 0xffff0000, v130
	v_pk_mul_f32 v[188:189], v[174:175], v[174:175]
	v_pk_mul_f32 v[190:191], v[178:179], v[178:179]
	s_waitcnt vmcnt(4)
	v_and_b32_e32 v145, 0xffff0000, v133
	v_and_b32_e32 v144, 0xffff0000, v132
	v_and_b32_e32 v147, 0xffff0000, v135
	v_and_b32_e32 v146, 0xffff0000, v134
	v_pk_mul_f32 v[192:193], v[140:141], v[140:141]
	v_pk_mul_f32 v[194:195], v[142:143], v[142:143]
	v_lshlrev_b32_e32 v120, 16, v68
	v_lshlrev_b32_e32 v124, 16, v69
	v_lshlrev_b32_e32 v122, 16, v70
	v_lshlrev_b32_e32 v126, 16, v71
	v_lshlrev_b32_e32 v68, 16, v64
	v_and_b32_e32 v69, 0xffff0000, v64
	v_lshlrev_b32_e32 v70, 16, v65
	v_and_b32_e32 v71, 0xffff0000, v65
	v_lshlrev_b32_e32 v64, 16, v66
	v_and_b32_e32 v65, 0xffff0000, v66
	v_lshlrev_b32_e32 v66, 16, v67
	v_and_b32_e32 v67, 0xffff0000, v67
	v_lshlrev_b32_e32 v181, 16, v129
	v_lshlrev_b32_e32 v180, 16, v128
	v_lshlrev_b32_e32 v185, 16, v131
	v_lshlrev_b32_e32 v184, 16, v130
	v_lshlrev_b32_e32 v149, 16, v133
	v_lshlrev_b32_e32 v148, 16, v132
	v_lshlrev_b32_e32 v151, 16, v135
	v_lshlrev_b32_e32 v150, 16, v134
	s_waitcnt vmcnt(3)
	v_lshlrev_b32_e32 v128, 16, v164
	v_and_b32_e32 v129, 0xffff0000, v164
	v_and_b32_e32 v131, 0xffff0000, v165
	v_lshlrev_b32_e32 v132, 16, v166
	v_and_b32_e32 v133, 0xffff0000, v166
	v_and_b32_e32 v135, 0xffff0000, v167
	s_waitcnt vmcnt(2)
	v_lshlrev_b32_e32 v72, 16, v168
	v_and_b32_e32 v73, 0xffff0000, v168
	v_lshlrev_b32_e32 v76, 16, v170
	v_and_b32_e32 v77, 0xffff0000, v170
	v_mul_f32_e32 v164, v121, v121
	v_mul_f32_e32 v166, v125, v125
	v_mul_f32_e32 v168, v123, v123
	v_mul_f32_e32 v170, v127, v127
	v_mov_b32_e32 v196, v172
	v_mov_b32_e32 v197, v174
	v_mov_b32_e32 v174, v173
	v_mov_b32_e32 v198, v176
	v_mov_b32_e32 v199, v178
	v_mov_b32_e32 v178, v177
	v_pk_mul_f32 v[200:201], v[182:183], v[182:183]
	v_pk_mul_f32 v[202:203], v[186:187], v[186:187]
	v_pk_fma_f32 v[172:173], v[172:173], v[172:173], v[188:189]
	v_pk_fma_f32 v[176:177], v[176:177], v[176:177], v[190:191]
	v_pk_mul_f32 v[188:189], v[144:145], v[144:145]
	v_pk_mul_f32 v[190:191], v[146:147], v[146:147]
	v_pk_fma_f32 v[192:193], v[136:137], v[136:137], v[192:193]
	v_pk_fma_f32 v[194:195], v[138:139], v[138:139], v[194:195]
	v_lshlrev_b32_e32 v130, 16, v165
	v_lshlrev_b32_e32 v134, 16, v167
	v_lshlrev_b32_e32 v74, 16, v169
	v_and_b32_e32 v75, 0xffff0000, v169
	v_lshlrev_b32_e32 v78, 16, v171
	v_and_b32_e32 v79, 0xffff0000, v171
	v_mul_f32_e32 v163, v68, v68
	v_mul_f32_e32 v216, v69, v69
	v_mul_f32_e32 v217, v70, v70
	v_mul_f32_e32 v218, v71, v71
	v_mul_f32_e32 v219, v64, v64
	v_mul_f32_e32 v220, v65, v65
	v_mul_f32_e32 v221, v66, v66
	v_mul_f32_e32 v222, v67, v67
	v_mul_f32_e32 v204, v129, v129
	v_mul_f32_e32 v206, v131, v131
	v_mul_f32_e32 v208, v133, v133
	v_mul_f32_e32 v210, v135, v135
	v_pk_fma_f32 v[164:165], v[120:121], v[120:121], v[164:165] op_sel_hi:[1,1,0]
	v_pk_fma_f32 v[166:167], v[124:125], v[124:125], v[166:167] op_sel_hi:[1,1,0]
	v_pk_fma_f32 v[168:169], v[122:123], v[122:123], v[168:169] op_sel_hi:[1,1,0]
	v_pk_fma_f32 v[170:171], v[126:127], v[126:127], v[170:171] op_sel_hi:[1,1,0]
	v_pk_fma_f32 v[200:201], v[180:181], v[180:181], v[200:201]
	v_pk_fma_f32 v[202:203], v[184:185], v[184:185], v[202:203]
	v_pk_fma_f32 v[188:189], v[148:149], v[148:149], v[188:189]
	v_pk_fma_f32 v[190:191], v[150:151], v[150:151], v[190:191]
	v_pk_add_f32 v[172:173], v[172:173], v[172:173] op_sel:[0,1] op_sel_hi:[1,0]
	v_pk_add_f32 v[176:177], v[176:177], v[176:177] op_sel:[0,1] op_sel_hi:[1,0]
	v_pk_add_f32 v[192:193], v[192:193], v[192:193] op_sel:[0,1] op_sel_hi:[1,0]
	v_pk_add_f32 v[194:195], v[194:195], v[194:195] op_sel:[0,1] op_sel_hi:[1,0]
	v_mul_f32_e32 v223, v72, v72
	v_mul_f32_e32 v224, v73, v73
	v_mul_f32_e32 v225, v74, v74
	v_mul_f32_e32 v226, v75, v75
	v_mul_f32_e32 v227, v76, v76
	v_mul_f32_e32 v228, v77, v77
	v_mul_f32_e32 v229, v78, v78
; __device__ __forceinline__ float bf_lo(unsigned w) { return __uint_as_float(w << 16); }
; __device__ __forceinline__ float bf_hi(unsigned w) { return __uint_as_float(w & 0xffff0000u); }
; #define LAS __attribute__((address_space(3)))
; __device__ __forceinline__ void phase12(const Args& a, LAS unsigned char* lds, int G, int wv, float* xout_base = nullptr) {
;     ...
;             const float ry = 1.0f / sqrtf(wave_sum(ssy) * (1.0f / 2048.0f) + EPS_), rf = 1.0f / sqrtf(wave_sum(ssf) * (1.0f / 2048.0f) + EPS_);
; #pragma unroll
;             for (int j = 0; j < 4; ++j) { const int c = 8 * (lane + 64 * j);
;                 const f32x4 xa = __builtin_nontemporal_load((const f32x4*)(xr + c)), xb = __builtin_nontemporal_load((const f32x4*)(xr + c + 4));
;                 const f32x4 g1a = *(const LAS f32x4*)(G1 + c), g1b = *(const LAS f32x4*)(G1 + c + 4), g2a = *(const LAS f32x4*)(G2 + c), g2b = *(const LAS f32x4*)(G2 + c + 4);
;                 const f32x4 ya = {bf_lo(yw[j].x), bf_hi(yw[j].x), bf_lo(yw[j].y), bf_hi(yw[j].y)}, yb = {bf_lo(yw[j].z), bf_hi(yw[j].z), bf_lo(yw[j].w), bf_hi(yw[j].w)};
;                 const f32x4 fa = {bf_lo(fw[j].x), bf_hi(fw[j].x), bf_lo(fw[j].y), bf_hi(fw[j].y)}, fb = {bf_lo(fw[j].z), bf_hi(fw[j].z), bf_lo(fw[j].w), bf_hi(fw[j].w)};
;                 const f32x4 x1a = xa + g1a * ya * ry, x1b = xb + g1b * yb * ry;
;                 *(f32x4*)(xo + c) = x1a + g2a * fa * rf; *(f32x4*)(xo + c + 4) = x1b + g2b * fb * rf; }
	v_mul_f32_e32 v230, v79, v79
	v_mov_b32_e32 v214, v185
	v_mov_b32_e32 v215, v187
	v_pk_fma_f32 v[204:205], v[128:129], v[128:129], v[204:205] op_sel_hi:[1,1,0]
	v_pk_fma_f32 v[206:207], v[130:131], v[130:131], v[206:207] op_sel_hi:[1,1,0]
	v_pk_fma_f32 v[208:209], v[132:133], v[132:133], v[208:209] op_sel_hi:[1,1,0]
	v_pk_fma_f32 v[210:211], v[134:135], v[134:135], v[210:211] op_sel_hi:[1,1,0]
	v_mov_b32_e32 v165, v219
	v_mov_b32_e32 v167, v220
	v_mov_b32_e32 v169, v221
	v_mov_b32_e32 v171, v222
	v_mov_b32_e32 v185, v186
	v_pk_add_f32 v[186:187], v[200:201], v[200:201] op_sel:[0,1] op_sel_hi:[1,0]
	v_pk_add_f32 v[200:201], v[202:203], v[202:203] op_sel:[0,1] op_sel_hi:[1,0]
	v_pk_add_f32 v[188:189], v[188:189], v[188:189] op_sel:[0,1] op_sel_hi:[1,0]
	v_pk_add_f32 v[190:191], v[190:191], v[190:191] op_sel:[0,1] op_sel_hi:[1,0]
	v_mov_b32_e32 v173, v163
	v_mov_b32_e32 v177, v216
	v_mov_b32_e32 v193, v217
	v_mov_b32_e32 v195, v218
	v_mov_b32_e32 v212, v181
	v_mov_b32_e32 v181, v182
	v_mov_b32_e32 v205, v227
	v_mov_b32_e32 v207, v228
	v_mov_b32_e32 v209, v229
	v_mov_b32_e32 v211, v230
	v_pk_add_f32 v[164:165], v[164:165], v[166:167]
	v_pk_add_f32 v[166:167], v[168:169], v[170:171]
	v_mov_b32_e32 v187, v223
	v_mov_b32_e32 v201, v224
	v_mov_b32_e32 v189, v225
	v_mov_b32_e32 v191, v226
	v_pk_add_f32 v[172:173], v[172:173], v[176:177]
	v_pk_add_f32 v[176:177], v[192:193], v[194:195]
	s_waitcnt lgkmcnt(14)
	v_pk_mul_f32 v[168:169], v[0:1], v[180:181]
	v_pk_mul_f32 v[170:171], v[4:5], v[184:185]
	v_pk_add_f32 v[180:181], v[204:205], v[206:207]
	v_pk_add_f32 v[184:185], v[208:209], v[210:211]
	v_pk_add_f32 v[164:165], v[164:165], v[166:167]
	v_pk_add_f32 v[166:167], v[186:187], v[200:201]
	v_pk_add_f32 v[186:187], v[188:189], v[190:191]
	v_pk_add_f32 v[172:173], v[172:173], v[176:177]
	v_pk_add_f32 v[180:181], v[180:181], v[184:185]
	v_pk_add_f32 v[166:167], v[166:167], v[186:187]
	v_pk_add_f32 v[164:165], v[172:173], v[164:165]
	v_pk_add_f32 v[166:167], v[166:167], v[180:181]
	v_add_f32_e32 v163, v164, v165
	v_add_f32_e32 v164, v166, v167
	ds_bpermute_b32 v165, v153, v163
	ds_bpermute_b32 v166, v153, v164
	v_mov_b32_e32 v213, v183
	v_pk_mul_f32 v[212:213], v[2:3], v[212:213]
	s_waitcnt lgkmcnt(14)
	v_pk_mul_f32 v[196:197], v[8:9], v[196:197]
	s_waitcnt lgkmcnt(1)
	v_add_f32_e32 v163, v163, v165
	s_waitcnt lgkmcnt(0)
	v_add_f32_e32 v164, v164, v166
	ds_bpermute_b32 v165, v154, v163
	ds_bpermute_b32 v166, v154, v164
	v_pk_mul_f32 v[174:175], v[10:11], v[174:175]
	v_pk_mul_f32 v[182:183], v[6:7], v[214:215]
	v_pk_mul_f32 v[198:199], v[12:13], v[198:199]
	s_waitcnt lgkmcnt(1)
	v_add_f32_e32 v163, v163, v165
	s_waitcnt lgkmcnt(0)
	v_add_f32_e32 v164, v164, v166
	ds_bpermute_b32 v165, v155, v163
	ds_bpermute_b32 v166, v155, v164
	v_pk_mul_f32 v[178:179], v[14:15], v[178:179]
	v_pk_mul_f32 v[128:129], v[32:33], v[128:129]
	v_pk_mul_f32 v[130:131], v[34:35], v[130:131]
	s_waitcnt lgkmcnt(1)
	v_add_f32_e32 v163, v163, v165
	s_waitcnt lgkmcnt(0)
	v_add_f32_e32 v164, v164, v166
	ds_bpermute_b32 v165, v156, v163
	ds_bpermute_b32 v166, v156, v164
	v_pk_mul_f32 v[124:125], v[42:43], v[124:125]
	v_pk_mul_f32 v[120:121], v[40:41], v[120:121]
	v_pk_mul_f32 v[132:133], v[36:37], v[132:133]
	s_waitcnt lgkmcnt(1)
	v_add_f32_e32 v163, v163, v165
	s_waitcnt lgkmcnt(0)
	v_add_f32_e32 v164, v164, v166
	ds_bpermute_b32 v165, v157, v163
	ds_bpermute_b32 v166, v157, v164
	v_pk_mul_f32 v[134:135], v[38:39], v[134:135]
	v_pk_mul_f32 v[126:127], v[46:47], v[126:127]
	v_pk_mul_f32 v[122:123], v[44:45], v[122:123]
	s_waitcnt lgkmcnt(1)
	v_add_f32_e32 v163, v163, v165
	s_waitcnt lgkmcnt(0)
	v_add_f32_e32 v164, v164, v166
	ds_bpermute_b32 v165, v158, v163
	ds_bpermute_b32 v166, v158, v164
	v_pk_mul_f32 v[70:71], v[58:59], v[70:71]
	v_pk_mul_f32 v[68:69], v[56:57], v[68:69]
	s_waitcnt lgkmcnt(1)
	v_add_f32_e32 v163, v163, v165
	s_waitcnt lgkmcnt(0)
	v_add_f32_e32 v164, v164, v166
	v_fmamk_f32 v163, v163, 0x3a000000, v161
	v_fmamk_f32 v164, v164, 0x3a000000, v161
	v_mul_f32_e32 v165, 0x4f800000, v163
	v_cmp_gt_f32_e32 vcc, s16, v163
	v_mul_f32_e32 v166, 0x4f800000, v164
	v_cmp_gt_f32_e64 s[0:1], s16, v164
	v_cndmask_b32_e32 v163, v163, v165, vcc
	v_sqrt_f32_e32 v165, v163
	v_cndmask_b32_e64 v164, v164, v166, s[0:1]
	v_sqrt_f32_e32 v166, v164
	v_add_u32_e32 v167, -1, v165
	v_add_u32_e32 v172, 1, v165
	v_add_u32_e32 v173, -1, v166
	v_fma_f32 v177, -v167, v165, v163
	v_add_u32_e32 v176, 1, v166
	v_fma_f32 v180, -v172, v165, v163
	v_fma_f32 v181, -v173, v166, v164
	v_cmp_ge_f32_e64 s[2:3], 0, v177
	v_fma_f32 v184, -v176, v166, v164
	v_cmp_ge_f32_e64 s[4:5], 0, v181
	v_cndmask_b32_e64 v165, v165, v167, s[2:3]
	v_cmp_lt_f32_e64 s[2:3], 0, v180
	v_cndmask_b32_e64 v166, v166, v173, s[4:5]
	s_nop 0
	v_cndmask_b32_e64 v165, v165, v172, s[2:3]
	v_cmp_lt_f32_e64 s[2:3], 0, v184
	v_mul_f32_e32 v167, 0x37800000, v165
	v_cndmask_b32_e32 v165, v165, v167, vcc
	v_cndmask_b32_e64 v166, v166, v176, s[2:3]
	v_mul_f32_e32 v172, 0x37800000, v166
	v_cmp_class_f32_e32 vcc, v163, v162
	v_cndmask_b32_e64 v166, v166, v172, s[0:1]
	s_nop 0
	v_cndmask_b32_e32 v163, v165, v163, vcc
	v_cmp_class_f32_e32 vcc, v164, v162
	v_div_scale_f32 v165, s[0:1], v163, v163, 1.0
	s_nop 0
	v_cndmask_b32_e32 v164, v166, v164, vcc
	v_div_scale_f32 v167, s[2:3], v164, v164, 1.0
	v_rcp_f32_e32 v173, v165
	v_rcp_f32_e32 v176, v167
	v_div_scale_f32 v166, s[0:1], 1.0, v163, 1.0
	v_fma_f32 v177, -v165, v173, 1.0
	v_fma_f32 v180, -v167, v176, 1.0
	v_div_scale_f32 v172, vcc, 1.0, v164, 1.0
	v_fmac_f32_e32 v173, v177, v173
	v_fmac_f32_e32 v176, v180, v176
	v_mul_f32_e32 v177, v166, v173
	v_mul_f32_e32 v180, v172, v176
	v_fma_f32 v181, -v165, v177, v166
	v_fma_f32 v184, -v167, v180, v172
	v_fmac_f32_e32 v177, v181, v173
	v_fmac_f32_e32 v180, v184, v176
	v_fma_f32 v165, -v165, v177, v166
	v_fma_f32 v166, -v167, v180, v172
	v_div_fmas_f32 v166, v166, v176, v180
	s_mov_b64 vcc, s[0:1]
	v_div_fixup_f32 v164, v166, v164, 1.0
	v_div_fmas_f32 v165, v165, v173, v177
	v_div_fixup_f32 v166, v165, v163, 1.0
	s_waitcnt vmcnt(0)
; __device__ __forceinline__ float bf_lo(unsigned w) { return __uint_as_float(w << 16); }
; __device__ __forceinline__ float bf_hi(unsigned w) { return __uint_as_float(w & 0xffff0000u); }
; #define LAS __attribute__((address_space(3)))
; __device__ __forceinline__ void phase12(const Args& a, LAS unsigned char* lds, int G, int wv, float* xout_base = nullptr) {
;     ...
; #pragma unroll
;             for (int j = 0; j < 4; ++j) { const int c = 8 * (lane + 64 * j);
;                 const f32x4 xa = __builtin_nontemporal_load((const f32x4*)(xr + c)), xb = __builtin_nontemporal_load((const f32x4*)(xr + c + 4));
;                 const f32x4 g1a = *(const LAS f32x4*)(G1 + c), g1b = *(const LAS f32x4*)(G1 + c + 4), g2a = *(const LAS f32x4*)(G2 + c), g2b = *(const LAS f32x4*)(G2 + c + 4);
;                 const f32x4 ya = {bf_lo(yw[j].x), bf_hi(yw[j].x), bf_lo(yw[j].y), bf_hi(yw[j].y)}, yb = {bf_lo(yw[j].z), bf_hi(yw[j].z), bf_lo(yw[j].w), bf_hi(yw[j].w)};
;                 const f32x4 fa = {bf_lo(fw[j].x), bf_hi(fw[j].x), bf_lo(fw[j].y), bf_hi(fw[j].y)}, fb = {bf_lo(fw[j].z), bf_hi(fw[j].z), bf_lo(fw[j].w), bf_hi(fw[j].w)};
;                 const f32x4 x1a = xa + g1a * ya * ry, x1b = xb + g1b * yb * ry;
;                 *(f32x4*)(xo + c) = x1a + g2a * fa * rf; *(f32x4*)(xo + c + 4) = x1b + g2b * fb * rf; }
	v_pk_fma_f32 v[84:85], v[168:169], v[164:165], v[84:85] op_sel_hi:[1,0,1]
	v_pk_fma_f32 v[86:87], v[212:213], v[164:165], v[86:87] op_sel_hi:[1,0,1]
	v_pk_fma_f32 v[168:169], v[170:171], v[164:165], v[80:81] op_sel_hi:[1,0,1]
	v_pk_fma_f32 v[170:171], v[182:183], v[164:165], v[82:83] op_sel_hi:[1,0,1]
	v_pk_fma_f32 v[82:83], v[174:175], v[166:167], v[86:87] op_sel_hi:[1,0,1]
	v_pk_fma_f32 v[80:81], v[196:197], v[166:167], v[84:85] op_sel_hi:[1,0,1]
	v_pk_fma_f32 v[86:87], v[178:179], v[166:167], v[170:171] op_sel_hi:[1,0,1]
	v_pk_fma_f32 v[84:85], v[198:199], v[166:167], v[168:169] op_sel_hi:[1,0,1]
	global_store_dwordx4 v[118:119], v[80:83], off nt
	global_store_dwordx4 v[118:119], v[84:87], off offset:16 nt
	global_load_dwordx4 v[80:83], v[116:117], off offset:2048 nt
	s_nop 0
	global_load_dwordx4 v[84:87], v[116:117], off offset:2064 nt
	v_mov_b32_e32 v176, v148
	v_mov_b32_e32 v177, v144
	v_mov_b32_e32 v144, v149
	v_mov_b32_e32 v172, v137
	v_mov_b32_e32 v173, v141
	v_mov_b32_e32 v174, v139
	v_mov_b32_e32 v175, v143
	v_mov_b32_e32 v148, v150
	v_mov_b32_e32 v149, v146
	v_mov_b32_e32 v146, v151
	v_mov_b32_e32 v137, v140
	v_mov_b32_e32 v139, v142
	v_pk_mul_f32 v[142:143], v[16:17], v[176:177]
	v_pk_mul_f32 v[144:145], v[18:19], v[144:145]
	v_pk_mul_f32 v[150:151], v[26:27], v[172:173]
	v_pk_mul_f32 v[148:149], v[20:21], v[148:149]
	v_pk_mul_f32 v[146:147], v[22:23], v[146:147]
	v_pk_mul_f32 v[136:137], v[24:25], v[136:137]
	v_add_co_u32_e32 v170, vcc, s17, v116
	v_pk_mul_f32 v[140:141], v[30:31], v[174:175]
	v_pk_mul_f32 v[138:139], v[28:29], v[138:139]
	v_addc_co_u32_e32 v171, vcc, 0, v117, vcc
	v_lshl_add_u64 v[168:169], v[116:117], 0, s[6:7]
	v_lshl_add_u64 v[116:117], v[116:117], 0, s[10:11]
	s_waitcnt vmcnt(1)
	v_pk_fma_f32 v[82:83], v[164:165], v[144:145], v[82:83] op_sel_hi:[0,1,1]
	v_pk_fma_f32 v[80:81], v[164:165], v[142:143], v[80:81] op_sel_hi:[0,1,1]
	s_waitcnt vmcnt(0)
	v_pk_fma_f32 v[86:87], v[164:165], v[146:147], v[86:87] op_sel_hi:[0,1,1]
	v_pk_fma_f32 v[84:85], v[164:165], v[148:149], v[84:85] op_sel_hi:[0,1,1]
	v_pk_fma_f32 v[80:81], v[166:167], v[136:137], v[80:81] op_sel_hi:[0,1,1]
	v_pk_fma_f32 v[82:83], v[166:167], v[150:151], v[82:83] op_sel_hi:[0,1,1]
	v_pk_fma_f32 v[84:85], v[166:167], v[138:139], v[84:85] op_sel_hi:[0,1,1]
	v_pk_fma_f32 v[86:87], v[166:167], v[140:141], v[86:87] op_sel_hi:[0,1,1]
	global_store_dwordx4 v[118:119], v[80:83], off offset:2048 nt
	global_store_dwordx4 v[118:119], v[84:87], off offset:2064 nt
	global_load_dwordx4 v[80:83], v[170:171], off nt
	s_nop 0
	global_load_dwordx4 v[84:87], v[168:169], off offset:16 nt
	v_add_co_u32_e32 v118, vcc, s17, v118
	s_waitcnt vmcnt(1)
	v_pk_fma_f32 v[82:83], v[164:165], v[130:131], v[82:83] op_sel_hi:[0,1,1]
	v_pk_fma_f32 v[80:81], v[164:165], v[128:129], v[80:81] op_sel_hi:[0,1,1]
	v_addc_co_u32_e32 v119, vcc, 0, v119, vcc
	s_waitcnt vmcnt(0)
	v_pk_fma_f32 v[86:87], v[164:165], v[134:135], v[86:87] op_sel_hi:[0,1,1]
	v_pk_fma_f32 v[84:85], v[164:165], v[132:133], v[84:85] op_sel_hi:[0,1,1]
	v_pk_fma_f32 v[80:81], v[166:167], v[120:121], v[80:81] op_sel_hi:[0,1,1]
	v_pk_fma_f32 v[82:83], v[166:167], v[124:125], v[82:83] op_sel_hi:[0,1,1]
	v_pk_fma_f32 v[84:85], v[166:167], v[122:123], v[84:85] op_sel_hi:[0,1,1]
	v_pk_fma_f32 v[86:87], v[166:167], v[126:127], v[86:87] op_sel_hi:[0,1,1]
	global_store_dwordx4 v[118:119], v[80:83], off nt
	global_store_dwordx4 v[118:119], v[84:87], off offset:16 nt
	global_load_dwordx4 v[80:83], v[170:171], off offset:2048 nt
	s_nop 0
	global_load_dwordx4 v[84:87], v[116:117], off offset:16 nt
	v_pk_mul_f32 v[116:117], v[62:63], v[66:67]
	v_pk_mul_f32 v[120:121], v[60:61], v[64:65]
	v_pk_mul_f32 v[64:65], v[48:49], v[72:73]
	v_pk_mul_f32 v[66:67], v[50:51], v[74:75]
	v_pk_mul_f32 v[72:73], v[52:53], v[76:77]
	v_pk_mul_f32 v[74:75], v[54:55], v[78:79]
	s_waitcnt vmcnt(1)
	v_pk_fma_f32 v[66:67], v[164:165], v[66:67], v[82:83] op_sel_hi:[0,1,1]
	v_pk_fma_f32 v[64:65], v[164:165], v[64:65], v[80:81] op_sel_hi:[0,1,1]
	s_waitcnt vmcnt(0)
	v_pk_fma_f32 v[74:75], v[164:165], v[74:75], v[86:87] op_sel_hi:[0,1,1]
	v_pk_fma_f32 v[72:73], v[164:165], v[72:73], v[84:85] op_sel_hi:[0,1,1]
	v_pk_fma_f32 v[64:65], v[166:167], v[68:69], v[64:65] op_sel_hi:[0,1,1]
	v_pk_fma_f32 v[66:67], v[166:167], v[70:71], v[66:67] op_sel_hi:[0,1,1]
	v_pk_fma_f32 v[68:69], v[166:167], v[120:121], v[72:73] op_sel_hi:[0,1,1]
	v_pk_fma_f32 v[70:71], v[166:167], v[116:117], v[74:75] op_sel_hi:[0,1,1]
	global_store_dwordx4 v[118:119], v[64:67], off offset:2048 nt
	global_store_dwordx4 v[118:119], v[68:71], off offset:2064 nt
	s_cbranch_scc0 .LBB0_1176
	s_add_i32 s14, s14, s15
	s_add_i32 s8, s8, s15
	s_cmpk_gt_i32 s14, 0x3fff
	s_cbranch_scc0 .LBB0_1175
